# v13 + nt on SGU V-tile loads
# speedup vs baseline: 1.0046x; 1.0001x over previous
.LBB0_623:
	s_or_b64 exec, exec, s[36:37]
	v_mov_b32_e32 v3, v56
	s_waitcnt lgkmcnt(0)
	s_barrier
	v_readlane_b32 s2, v252, 44
	v_lshlrev_b32_e32 v5, 4, v3
	v_lshlrev_b32_e32 v2, 8, v3
	v_and_b32_e32 v4, 0x1f0, v5
	s_movk_i32 s1, 0xe000
	s_waitcnt vmcnt(0)
	v_readlane_b32 s3, v252, 45
	v_and_or_b32 v129, v2, s1, v4
	s_nop 4
	global_load_dwordx4 v[18:21], v129, s[2:3] nt
	v_readlane_b32 s2, v252, 32
	v_readlane_b32 s3, v252, 33
	s_nop 4
	global_load_dwordx4 v[22:25], v129, s[2:3] nt
	v_readlane_b32 s2, v252, 34
	v_readlane_b32 s3, v252, 35
	s_nop 4
	global_load_dwordx4 v[26:29], v129, s[2:3] nt
	v_readlane_b32 s2, v252, 36
	v_readlane_b32 s3, v252, 37
	s_nop 4
	global_load_dwordx4 v[30:33], v129, s[2:3] nt
	v_readlane_b32 s2, v252, 38
	v_readlane_b32 s3, v252, 39
	s_nop 4
	global_load_dwordx4 v[34:37], v129, s[2:3] nt
	v_readlane_b32 s2, v252, 40
	v_readlane_b32 s3, v252, 41
	s_nop 4
	global_load_dwordx4 v[38:41], v129, s[2:3] nt
	v_readlane_b32 s2, v252, 42
	v_readfirstlane_b32 s0, v3
	v_readlane_b32 s3, v252, 43
	s_ashr_i32 s0, s0, 6
	s_nop 4
	global_load_dwordx4 v[42:45], v129, s[2:3] nt
	v_readlane_b32 s2, v252, 46
	v_bfe_u32 v128, v3, 2, 4
	s_lshl_b32 s4, s0, 5
	v_lshlrev_b32_e32 v7, 3, v3
	v_readlane_b32 s3, v252, 47
	v_lshl_add_u32 v6, v128, 12, s4
	v_and_b32_e32 v2, 24, v7
	s_nop 4
	global_load_dwordx4 v[46:49], v129, s[2:3] nt
	v_readlane_b32 s2, v252, 48
	v_or_b32_e32 v8, v6, v2
	v_and_b32_e32 v6, 0x7f, v3
	v_readlane_b32 s3, v252, 49
	v_lshlrev_b32_e32 v131, 3, v6
	s_nop 4
	global_load_dwordx2 v[118:119], v131, s[2:3]
	v_readlane_b32 s2, v252, 62
	v_readlane_b32 s3, v252, 63
	v_lshlrev_b32_e32 v130, 1, v8
	s_nop 4
	global_load_dwordx4 v[78:81], v130, s[2:3]
	v_readlane_b32 s2, v252, 50
	v_readlane_b32 s3, v252, 51
	s_nop 4
	global_load_dwordx4 v[74:77], v130, s[2:3]
	v_readlane_b32 s2, v252, 52
	v_readlane_b32 s3, v252, 53
	s_nop 4
	global_load_dwordx4 v[70:73], v130, s[2:3]
	v_readlane_b32 s2, v252, 54
	v_readlane_b32 s3, v252, 55
	s_nop 4
	global_load_dwordx4 v[66:69], v130, s[2:3]
	v_readlane_b32 s2, v252, 56
	v_readlane_b32 s3, v252, 57
	s_nop 4
	global_load_dwordx4 v[62:65], v130, s[2:3]
	v_readlane_b32 s2, v252, 58
	v_readlane_b32 s3, v252, 59
	s_nop 4
	global_load_dwordx4 v[58:61], v130, s[2:3]
	v_readlane_b32 s2, v252, 60
	v_readlane_b32 s3, v252, 61
	s_nop 4
	global_load_dwordx4 v[54:57], v130, s[2:3]
	v_readlane_b32 s2, v253, 0
	v_readlane_b32 s3, v253, 1
	s_nop 4
	global_load_dwordx4 v[50:53], v130, s[2:3]
	s_waitcnt vmcnt(8)
	s_and_b64 vcc, exec, s[72:73]
	s_cbranch_vccz .LBB0_633
	v_readlane_b32 s5, v254, 58
	s_lshl_b32 s1, s5, 19
	v_readlane_b32 s2, v252, 30
	v_readlane_b32 s3, v252, 31
	s_add_u32 s2, s2, s1
	s_addc_u32 s3, s3, 0
	s_lshl_b32 s86, s5, 12
	v_readlane_b32 s16, v251, 14
	s_lshl_b64 s[6:7], s[86:87], 2
	v_readlane_b32 s24, v251, 22
	v_readlane_b32 s25, v251, 23
	s_add_u32 s10, s24, s6
	s_addc_u32 s11, s25, s7
	s_lshl_b32 s86, s5, 11
	v_readlane_b32 s30, v251, 28
	s_lshl_b64 s[8:9], s[86:87], 2
	v_readlane_b32 s31, v251, 29
	s_add_u32 s8, s30, s8
	v_and_b32_e32 v8, 63, v3
	v_readlane_b32 s26, v251, 24
	s_addc_u32 s9, s31, s9
	v_readlane_b32 s27, v251, 25
	s_add_u32 s6, s26, s6
	v_lshrrev_b32_e32 v13, 5, v8
	v_ashrrev_i32_e32 v8, 4, v3
	s_addc_u32 s7, s27, s7
	s_mulk_i32 s0, 0x2400
	v_ashrrev_i32_e32 v9, 31, v8
	s_ashr_i32 s5, s4, 31
	s_add_i32 s14, s0, 0
	v_lshlrev_b64 v[10:11], 8, v[8:9]
	s_lshl_b64 s[0:1], s[4:5], 2
	v_lshl_add_u64 v[10:11], s[2:3], 0, v[10:11]
	v_and_b32_e32 v7, 0x78, v7
	s_add_u32 s2, s10, s0
	v_lshlrev_b32_e32 v202, 1, v7
	s_addc_u32 s3, s11, s1
	v_and_b32_e32 v12, 31, v3
	v_lshl_add_u64 v[120:121], v[10:11], 0, v[202:203]
	v_lshlrev_b32_e32 v202, 2, v6
	s_add_u32 s0, s6, s0
	v_lshl_add_u64 v[122:123], s[8:9], 0, v[202:203]
	v_lshlrev_b32_e32 v202, 2, v12
	s_addc_u32 s1, s7, s1
	v_lshl_add_u64 v[126:127], s[0:1], 0, v[202:203]
	s_movk_i32 s1, 0x80
	v_lshl_add_u64 v[124:125], s[2:3], 0, v[202:203]
	v_cmp_gt_i32_e64 s[2:3], s1, v3
	s_lshl_b32 s1, s4, 2
	v_readlane_b32 s7, v254, 55
	s_add_i32 s1, s7, s1
	v_and_b32_e32 v5, 0xf0, v5
	s_add_i32 s0, 0, 0x12000
	v_readlane_b32 s6, v254, 54
	v_add_u32_e32 v133, s1, v202
	v_readlane_b32 s1, v254, 56
	v_lshlrev_b32_e32 v7, 4, v13
	v_add_u32_e32 v14, 0x200, v3
	v_add_u32_e32 v16, 0x400, v3
	v_add_u32_e32 v82, 0x600, v3
	v_add_u32_e32 v5, s0, v5
	v_lshl_add_u32 v132, v3, 2, s6
	v_lshl_add_u32 v134, v3, 3, s1
	v_add_u32_e32 v9, s0, v7
	s_movk_i32 s0, 0x110
	v_lshrrev_b32_e32 v15, 4, v14
	v_lshrrev_b32_e32 v17, 4, v16
	v_lshrrev_b32_e32 v83, 4, v82
	v_ashrrev_i32_e32 v84, 5, v3
	v_add_u32_e32 v85, 0x800, v3
	v_add_u32_e32 v86, 0xa00, v3
	v_add_u32_e32 v87, 0xc00, v3
	v_add_u32_e32 v3, 0xe00, v3
	v_or_b32_e32 v6, s4, v12
	v_mul_lo_u32 v8, v8, s0
	v_mul_lo_u32 v15, v15, s0
	v_mul_lo_u32 v17, v17, s0
	v_mul_lo_u32 v83, v83, s0
	s_movk_i32 s0, 0x210
	v_ashrrev_i32_e32 v14, 5, v14
	v_ashrrev_i32_e32 v16, 5, v16
	v_ashrrev_i32_e32 v82, 5, v82
	v_ashrrev_i32_e32 v85, 5, v85
	v_ashrrev_i32_e32 v86, 5, v86
	v_ashrrev_i32_e32 v87, 5, v87
	v_ashrrev_i32_e32 v3, 5, v3
	v_lshl_add_u32 v136, v13, 6, s1
	v_mul_u32_u24_e32 v88, 0x1080, v13
	v_lshl_or_b32 v89, v13, 3, 1
	v_mov_b32_e32 v91, 0xc60
	v_mov_b32_e32 v92, 0x2940
	v_mov_b32_e32 v93, 0x4620
	v_mov_b32_e32 v94, 0x6300
	v_mul_u32_u24_e32 v95, 0x240, v13
	v_lshl_or_b32 v13, v13, 2, 1
	v_readlane_b32 s17, v251, 15
	v_readlane_b32 s18, v251, 16
	v_add_u32_e32 v4, 0, v4
	v_lshl_add_u32 v135, v6, 2, s7
	v_lshl_add_u32 v6, v6, 1, 0
	v_add_u32_e32 v10, s14, v202
	v_lshl_add_u32 v11, v2, 2, s14
	v_mul_lo_u32 v84, v84, s0
	v_mul_lo_u32 v14, v14, s0
	v_mul_lo_u32 v16, v16, s0
	v_mul_lo_u32 v82, v82, s0
	v_mul_lo_u32 v85, v85, s0
	v_mul_lo_u32 v86, v86, s0
	v_mul_lo_u32 v87, v87, s0
	v_mul_lo_u32 v3, v3, s0
	v_mul_u32_u24_e32 v90, 0x210, v89
	v_mad_u32_u24 v91, v89, s0, v91
	v_mad_u32_u24 v92, v89, s0, v92
	v_mad_u32_u24 v93, v89, s0, v93
	v_mad_u32_u24 v89, v89, s0, v94
	v_mul_u32_u24_e32 v94, 0x90, v128
	v_mul_u32_u24_e32 v12, 0x110, v12
	v_lshlrev_b32_e32 v96, 2, v13
	v_mul_u32_u24_e32 v13, 0x90, v13
	v_or_b32_e32 v97, 8, v7
	v_or_b32_e32 v98, 12, v7
	v_or_b32_e32 v99, 32, v7
	v_or_b32_e32 v100, 36, v7
	v_or_b32_e32 v101, 40, v7
	v_or_b32_e32 v102, 44, v7
	v_or_b32_e32 v103, 64, v7
	v_or_b32_e32 v104, 0x44, v7
	v_or_b32_e32 v105, 0x48, v7
	v_or_b32_e32 v106, 0x4c, v7
	v_or_b32_e32 v107, 0x60, v7
	v_or_b32_e32 v108, 0x64, v7
	v_or_b32_e32 v109, 0x68, v7
	v_or_b32_e32 v110, 0x6c, v7
	v_or_b32_e32 v111, 0x80, v7
	v_or_b32_e32 v112, 0x84, v7
	v_or_b32_e32 v113, 0x88, v7
	v_or_b32_e32 v114, 0x8c, v7
	v_or_b32_e32 v115, 0xa0, v7
	v_or_b32_e32 v116, 0xa4, v7
	v_or_b32_e32 v117, 0xa8, v7
	v_or_b32_e32 v202, 0xac, v7
	v_or_b32_e32 v204, 0xc0, v7
	v_or_b32_e32 v205, 0xc4, v7
	v_or_b32_e32 v206, 0xc8, v7
	v_or_b32_e32 v207, 0xcc, v7
	v_or_b32_e32 v223, 0xe0, v7
	v_or_b32_e32 v224, 0xe4, v7
	v_or_b32_e32 v225, 0xe8, v7
	v_or_b32_e32 v226, 0xec, v7
	v_readlane_b32 s0, v254, 57
	v_add_u32_e32 v137, 0x180, v136
	v_add_u32_e32 v138, 0x190, v136
	v_add_u32_e32 v139, 0x1a0, v136
	v_add_u32_e32 v140, 0x1b0, v136
	v_add_u32_e32 v141, 0x200, v136
	v_add_u32_e32 v142, 0x210, v136
	v_add_u32_e32 v143, 0x220, v136
	v_add_u32_e32 v144, 0x230, v136
	v_add_u32_e32 v145, 0x280, v136
	v_add_u32_e32 v146, 0x290, v136
	v_add_u32_e32 v147, 0x2a0, v136
	v_add_u32_e32 v148, 0x2b0, v136
	v_add_u32_e32 v149, 0x300, v136
	v_add_u32_e32 v150, 0x310, v136
	v_add_u32_e32 v151, 0x320, v136
	v_add_u32_e32 v152, 0x330, v136
	v_add_u32_e32 v153, 0x380, v136
	v_add_u32_e32 v154, 0x390, v136
	v_add_u32_e32 v155, 0x3a0, v136
	v_add_u32_e32 v156, 0x3b0, v136
	v_add_u32_e32 v157, s6, v7
	v_add_u32_e32 v158, s6, v96
	v_add_u32_e32 v159, s6, v97
	v_add_u32_e32 v160, s6, v98
	v_add_u32_e32 v161, s6, v99
	v_add_u32_e32 v162, s6, v100
	v_add_u32_e32 v163, s6, v101
	v_add_u32_e32 v164, s6, v102
	v_add_u32_e32 v165, s6, v103
	v_add_u32_e32 v166, s6, v104
	v_add_u32_e32 v167, s6, v105
	v_add_u32_e32 v168, s6, v106
	v_add_u32_e32 v169, s6, v107
	v_add_u32_e32 v170, s6, v108
	v_add_u32_e32 v171, s6, v109
	v_add_u32_e32 v172, s6, v110
	v_add_u32_e32 v173, s6, v111
	v_add_u32_e32 v174, s6, v112
	v_add_u32_e32 v175, s6, v113
	v_add_u32_e32 v176, s6, v114
	v_add_u32_e32 v177, s6, v115
	v_add_u32_e32 v178, s6, v116
	v_add_u32_e32 v179, s6, v117
	v_add_u32_e32 v180, s6, v202
	v_add_u32_e32 v181, s6, v204
	v_add_u32_e32 v182, s6, v205
	v_add_u32_e32 v183, s6, v206
	v_add_u32_e32 v184, s6, v207
	v_add_u32_e32 v185, s6, v223
	v_add_u32_e32 v186, s6, v224
	v_add_u32_e32 v187, s6, v225
	v_add_u32_e32 v188, s6, v226
	v_add_u32_e32 v189, s0, v7
	v_add_u32_e32 v190, s0, v96
	v_add_u32_e32 v191, s0, v97
	v_add_u32_e32 v192, s0, v98
	v_add_u32_e32 v193, s0, v99
	v_add_u32_e32 v194, s0, v100
	v_add_u32_e32 v195, s0, v101
	v_add_u32_e32 v196, s0, v102
	v_add_u32_e32 v197, s0, v103
	v_add_u32_e32 v198, s0, v104
	v_add_u32_e32 v199, s0, v105
	v_add_u32_e32 v200, s0, v106
	v_add_u32_e32 v201, s0, v107
	v_add_u32_e32 v208, s0, v108
	v_add_u32_e32 v209, s0, v109
	v_add_u32_e32 v210, s0, v110
	v_add_u32_e32 v211, s0, v111
	v_add_u32_e32 v212, s0, v112
	v_add_u32_e32 v213, s0, v113
	v_add_u32_e32 v214, s0, v114
	v_add_u32_e32 v215, s0, v115
	v_add_u32_e32 v216, s0, v116
	v_add_u32_e32 v217, s0, v117
	v_add_u32_e32 v218, s0, v202
	v_add_u32_e32 v219, s0, v204
	v_add_u32_e32 v220, s0, v205
	v_add_u32_e32 v221, s0, v206
	v_add_u32_e32 v222, s0, v207
	v_add_u32_e32 v223, s0, v223
	v_add_u32_e32 v224, s0, v224
	v_add_u32_e32 v225, s0, v225
	v_add_u32_e32 v226, s0, v226
	s_lshl_b32 s14, s96, 8
	s_lshl_b32 s15, s96, 7
	s_mov_b32 s18, -1
	v_add_u32_e32 v227, v5, v8
	v_add_u32_e32 v228, v5, v15
	v_add_u32_e32 v229, v5, v17
	v_add_u32_e32 v230, v5, v83
	v_add_u32_e32 v231, v4, v84
	v_add_u32_e32 v232, v4, v14
	v_add_u32_e32 v233, v4, v16
	v_add_u32_e32 v238, v4, v82
	v_add_u32_e32 v239, v4, v85
	v_add_u32_e32 v240, v4, v86
	v_add_u32_e32 v241, v4, v87
	v_add_u32_e32 v242, v4, v3
	v_add_u32_e32 v243, v6, v88
	v_add_u32_e32 v244, v6, v90
	v_add_u32_e32 v245, v6, v91
	v_add_u32_e32 v246, v6, v92
	v_add_u32_e32 v247, v6, v93
	v_add_u32_e32 v248, v6, v89
	v_lshlrev_b32_e32 v202, 1, v2
	v_add_u32_e32 v249, v9, v12
	v_add_u32_e32 v250, v10, v95
	v_add_u32_e32 v204, v10, v13
	v_add_u32_e32 v205, v11, v94
	v_readlane_b32 s16, v254, 31
	v_readlane_b32 s17, v254, 30
	s_mov_b32 s10, s84
	s_mov_b32 s57, 0x20000
	s_mov_b32 s88, 0x40000
	v_readlane_b32 s19, v251, 17
	v_readlane_b32 s20, v251, 18
	v_readlane_b32 s21, v251, 19
	v_readlane_b32 s22, v251, 20
	v_readlane_b32 s23, v251, 21
	v_readlane_b32 s28, v251, 26
	v_readlane_b32 s29, v251, 27

.LBB0_629:
	s_and_saveexec_b64 s[6:7], s[2:3]
	ds_write_b64 v134, v[118:119]
	s_or_b64 exec, exec, s[6:7]
	s_add_i32 s19, s10, s96
	s_cmpk_lt_i32 s19, 0x840
	s_cselect_b64 s[6:7], -1, 0
	s_and_b64 s[0:1], s[6:7], exec
	s_cselect_b32 s0, s19, s10
	s_ashr_i32 s1, s0, 31
	s_lshr_b32 s1, s1, 28
	s_add_i32 s1, s0, s1
	s_and_b32 s8, s1, 0xfffff0
	s_sub_i32 s10, s0, s8
	s_lshl_b32 s0, s1, 3
	s_and_b32 s0, s0, 0xffffff80
	s_ashr_i32 s1, s0, 31
	s_lshl_b64 s[8:9], s[0:1], 13
	v_readlane_b32 s22, v252, 0
	v_readlane_b32 s23, v252, 1
	s_add_u32 s21, s22, s8
	s_addc_u32 s23, s23, s9
	s_lshl_b32 s10, s10, 8
	s_ashr_i32 s11, s10, 31
	s_lshl_b64 s[10:11], s[10:11], 1
	s_add_u32 s22, s21, s10
	s_addc_u32 s23, s23, s11
	s_add_u32 s24, s22, 0x20000
	ds_write_b128 v231, v[18:21]
	ds_write_b128 v232, v[22:25]
	ds_write_b128 v233, v[26:29]
	ds_write_b128 v238, v[30:33]
	ds_write_b128 v239, v[34:37]
	ds_write_b128 v240, v[38:41]
	ds_write_b128 v241, v[42:45]
	ds_write_b128 v242, v[46:49]
	s_waitcnt lgkmcnt(0)
	s_barrier
	s_nop 4
	global_load_dwordx4 v[18:21], v129, s[22:23] nt
	s_addc_u32 s25, s23, 0
	s_nop 4
	global_load_dwordx4 v[22:25], v129, s[24:25] nt
	s_add_u32 s24, s22, 0x40000
	s_addc_u32 s25, s23, 0
	s_nop 4
	global_load_dwordx4 v[26:29], v129, s[24:25] nt
	s_add_u32 s24, s22, 0x60000
	s_addc_u32 s25, s23, 0
	s_nop 4
	global_load_dwordx4 v[30:33], v129, s[24:25] nt
	s_add_u32 s24, s22, 0x80000
	s_addc_u32 s25, s23, 0
	s_nop 4
	global_load_dwordx4 v[34:37], v129, s[24:25] nt
	s_add_u32 s24, s22, 0xa0000
	s_addc_u32 s25, s23, 0
	s_nop 4
	global_load_dwordx4 v[38:41], v129, s[24:25] nt
	s_add_u32 s24, s22, 0xc0000
	s_addc_u32 s25, s23, 0
	s_add_u32 s22, s22, 0xe0000
	s_nop 4
	global_load_dwordx4 v[42:45], v129, s[24:25] nt
	s_addc_u32 s23, s23, 0
	s_lshl_b64 s[0:1], s[0:1], 3
	s_nop 4
	global_load_dwordx4 v[46:49], v129, s[22:23] nt
	s_add_u32 s0, s12, s0
	s_addc_u32 s1, s83, s1
	s_nop 4
	global_load_dwordx2 v[118:119], v131, s[0:1]
	v_add_u32_e32 v6, 16, v136
	ds_read_b32 v110, v135
	ds_read_b32 v112, v133 offset:1024
	ds_read_b128 v[2:5], v136
	ds_read_u16 v82, v243
	ds_read_u16 v86, v244
	ds_read_b128 v[6:9], v6
	ds_read_u16 v83, v244 offset:528
	ds_read_u16 v87, v244 offset:1056
	v_add_u32_e32 v10, 32, v136
	v_add_u32_e32 v14, 48, v136
	ds_read_b128 v[10:13], v10
	ds_read_u16 v88, v244 offset:1584
	ds_read_u16 v89, v244 offset:2112
	ds_read_b128 v[14:17], v14
	ds_read_u16 v90, v244 offset:2640
	ds_read_u16 v91, v245
	s_waitcnt lgkmcnt(0)
	v_lshlrev_b32_e32 v83, 16, v83
	v_lshlrev_b32_e32 v82, 16, v82
	v_mov_b32_e32 v84, v2
	v_mov_b32_e32 v85, v6
	v_pk_add_f32 v[82:83], v[82:83], v[84:85] neg_lo:[0,1] neg_hi:[0,1]
	v_mov_b32_e32 v6, v3
	v_pk_mul_f32 v[2:3], v[6:7], v[82:83]
	v_lshlrev_b32_e32 v7, 16, v87
	v_lshlrev_b32_e32 v6, 16, v86
	v_mov_b32_e32 v82, v4
	v_mov_b32_e32 v83, v8
	v_pk_add_f32 v[6:7], v[6:7], v[82:83] neg_lo:[0,1] neg_hi:[0,1]
	v_mov_b32_e32 v8, v5
	v_pk_mul_f32 v[4:5], v[8:9], v[6:7]
	v_lshlrev_b32_e32 v7, 16, v90
	v_lshlrev_b32_e32 v6, 16, v88
	v_mov_b32_e32 v8, v10
	v_mov_b32_e32 v9, v14
	v_pk_add_f32 v[6:7], v[6:7], v[8:9] neg_lo:[0,1] neg_hi:[0,1]
	v_mov_b32_e32 v14, v11
	v_lshlrev_b32_e32 v9, 16, v91
	v_lshlrev_b32_e32 v8, 16, v89
	v_mov_b32_e32 v10, v12
	v_mov_b32_e32 v11, v16
	v_pk_add_f32 v[8:9], v[8:9], v[10:11] neg_lo:[0,1] neg_hi:[0,1]
	v_mov_b32_e32 v16, v13
	v_pk_mul_f32 v[8:9], v[16:17], v[8:9]
	v_pk_fma_f32 v[4:5], v[110:111], v[4:5], v[112:113] op_sel_hi:[0,1,0]
	v_pk_mul_f32 v[6:7], v[14:15], v[6:7]
	v_pk_fma_f32 v[8:9], v[110:111], v[8:9], v[112:113] op_sel_hi:[0,1,0]
	v_pk_fma_f32 v[2:3], v[110:111], v[2:3], v[112:113] op_sel_hi:[0,1,0]
	v_pk_fma_f32 v[6:7], v[110:111], v[6:7], v[112:113] op_sel_hi:[0,1,0]
	v_bfe_u32 v10, v9, 16, 1
	v_bfe_u32 v12, v5, 16, 1
	v_bfe_u32 v11, v8, 16, 1
	v_bfe_u32 v13, v4, 16, 1
	v_add3_u32 v5, v5, v12, s53
	v_add3_u32 v9, v9, v10, s53
	v_bfe_u32 v10, v2, 16, 1
	v_bfe_u32 v12, v6, 16, 1
	v_add3_u32 v4, v4, v13, s53
	v_add3_u32 v8, v8, v11, s53
	v_bfe_u32 v11, v3, 16, 1
	v_bfe_u32 v13, v7, 16, 1
	v_add3_u32 v6, v6, v12, s53
	v_add3_u32 v2, v2, v10, s53
	v_add3_u32 v7, v7, v13, s53
	v_add3_u32 v3, v3, v11, s53
	v_lshrrev_b32_e32 v2, 16, v2
	v_lshrrev_b32_e32 v6, 16, v6
	v_lshrrev_b32_e32 v3, 16, v3
	v_lshrrev_b32_e32 v7, 16, v7
	v_and_or_b32 v84, v8, s77, v6
	v_and_or_b32 v82, v4, s77, v2
	v_add_u32_e32 v2, 0x80, v136
	v_add_u32_e32 v6, 0x90, v136
	v_and_or_b32 v85, v9, s77, v7
	v_and_or_b32 v83, v5, s77, v3
	ds_read_b128 v[2:5], v2
	ds_read_u16 v86, v245 offset:4752
	ds_read_u16 v90, v245 offset:5280
	ds_read_b128 v[6:9], v6
	ds_read_u16 v87, v245 offset:5808
	ds_read_u16 v91, v245 offset:6336
	v_add_u32_e32 v10, 0xa0, v136
	v_add_u32_e32 v14, 0xb0, v136
	ds_read_b128 v[10:13], v10
	ds_read_u16 v92, v245 offset:6864
	ds_read_u16 v93, v246
	ds_read_b128 v[14:17], v14
	ds_read_u16 v94, v246 offset:528
	ds_read_u16 v95, v246 offset:1056
	s_waitcnt lgkmcnt(0)
	v_lshlrev_b32_e32 v87, 16, v87
	v_lshlrev_b32_e32 v86, 16, v86
	v_mov_b32_e32 v88, v2
	v_mov_b32_e32 v89, v6
	v_pk_add_f32 v[86:87], v[86:87], v[88:89] neg_lo:[0,1] neg_hi:[0,1]
	v_mov_b32_e32 v6, v3
	v_pk_mul_f32 v[2:3], v[6:7], v[86:87]
	v_lshlrev_b32_e32 v7, 16, v91
	v_lshlrev_b32_e32 v6, 16, v90
	v_mov_b32_e32 v86, v4
	v_mov_b32_e32 v87, v8
	v_pk_add_f32 v[6:7], v[6:7], v[86:87] neg_lo:[0,1] neg_hi:[0,1]
	v_mov_b32_e32 v8, v5
	v_pk_mul_f32 v[4:5], v[8:9], v[6:7]
	v_lshlrev_b32_e32 v7, 16, v94
	v_lshlrev_b32_e32 v6, 16, v92
	v_mov_b32_e32 v8, v10
	v_mov_b32_e32 v9, v14
	v_pk_add_f32 v[6:7], v[6:7], v[8:9] neg_lo:[0,1] neg_hi:[0,1]
	v_mov_b32_e32 v14, v11
	v_lshlrev_b32_e32 v9, 16, v95
	v_lshlrev_b32_e32 v8, 16, v93
	v_mov_b32_e32 v10, v12
	v_mov_b32_e32 v11, v16
	v_pk_add_f32 v[8:9], v[8:9], v[10:11] neg_lo:[0,1] neg_hi:[0,1]
	v_mov_b32_e32 v16, v13
	v_pk_mul_f32 v[8:9], v[16:17], v[8:9]
	v_pk_fma_f32 v[4:5], v[110:111], v[4:5], v[112:113] op_sel_hi:[0,1,0]
	v_pk_mul_f32 v[6:7], v[14:15], v[6:7]
	v_pk_fma_f32 v[8:9], v[110:111], v[8:9], v[112:113] op_sel_hi:[0,1,0]
	v_pk_fma_f32 v[2:3], v[110:111], v[2:3], v[112:113] op_sel_hi:[0,1,0]
	v_pk_fma_f32 v[6:7], v[110:111], v[6:7], v[112:113] op_sel_hi:[0,1,0]
	v_bfe_u32 v10, v9, 16, 1
	v_bfe_u32 v12, v5, 16, 1
	v_bfe_u32 v11, v8, 16, 1
	v_bfe_u32 v13, v4, 16, 1
	v_add3_u32 v5, v5, v12, s53
	v_add3_u32 v9, v9, v10, s53
	v_bfe_u32 v10, v2, 16, 1
	v_bfe_u32 v12, v6, 16, 1
	v_add3_u32 v4, v4, v13, s53
	v_add3_u32 v8, v8, v11, s53
	v_bfe_u32 v11, v3, 16, 1
	v_bfe_u32 v13, v7, 16, 1
	v_add3_u32 v6, v6, v12, s53
	v_add3_u32 v2, v2, v10, s53
	v_add3_u32 v7, v7, v13, s53
	v_add3_u32 v3, v3, v11, s53
	v_lshrrev_b32_e32 v2, 16, v2
	v_lshrrev_b32_e32 v6, 16, v6
	v_lshrrev_b32_e32 v3, 16, v3
	v_lshrrev_b32_e32 v7, 16, v7
	v_and_or_b32 v88, v8, s77, v6
	v_and_or_b32 v86, v4, s77, v2
	v_add_u32_e32 v2, 0x100, v136
	v_add_u32_e32 v6, 0x110, v136
	v_and_or_b32 v89, v9, s77, v7
	v_and_or_b32 v87, v5, s77, v3
	ds_read_b128 v[2:5], v2
	ds_read_u16 v90, v246 offset:5808
	ds_read_u16 v94, v246 offset:6336
	ds_read_b128 v[6:9], v6
	ds_read_u16 v91, v246 offset:6864
	ds_read_u16 v95, v247
	v_add_u32_e32 v10, 0x120, v136
	v_add_u32_e32 v14, 0x130, v136
	ds_read_b128 v[10:13], v10
	ds_read_u16 v96, v247 offset:528
	ds_read_u16 v97, v247 offset:1056
	ds_read_b128 v[14:17], v14
	ds_read_u16 v98, v247 offset:1584
	ds_read_u16 v99, v247 offset:2112
	s_waitcnt lgkmcnt(0)
	v_lshlrev_b32_e32 v91, 16, v91
	v_lshlrev_b32_e32 v90, 16, v90
	v_mov_b32_e32 v92, v2
	v_mov_b32_e32 v93, v6
	v_pk_add_f32 v[90:91], v[90:91], v[92:93] neg_lo:[0,1] neg_hi:[0,1]
	v_mov_b32_e32 v6, v3
	v_pk_mul_f32 v[2:3], v[6:7], v[90:91]
	v_lshlrev_b32_e32 v7, 16, v95
	v_lshlrev_b32_e32 v6, 16, v94
	v_mov_b32_e32 v90, v4
	v_mov_b32_e32 v91, v8
	v_pk_add_f32 v[6:7], v[6:7], v[90:91] neg_lo:[0,1] neg_hi:[0,1]
	v_mov_b32_e32 v8, v5
	v_pk_mul_f32 v[4:5], v[8:9], v[6:7]
	v_lshlrev_b32_e32 v7, 16, v98
	v_lshlrev_b32_e32 v6, 16, v96
	v_mov_b32_e32 v8, v10
	v_mov_b32_e32 v9, v14
	v_pk_add_f32 v[6:7], v[6:7], v[8:9] neg_lo:[0,1] neg_hi:[0,1]
	v_mov_b32_e32 v14, v11
	v_lshlrev_b32_e32 v9, 16, v99
	v_lshlrev_b32_e32 v8, 16, v97
	v_mov_b32_e32 v10, v12
	v_mov_b32_e32 v11, v16
	v_pk_add_f32 v[8:9], v[8:9], v[10:11] neg_lo:[0,1] neg_hi:[0,1]
	v_mov_b32_e32 v16, v13
	v_pk_mul_f32 v[8:9], v[16:17], v[8:9]
	v_pk_fma_f32 v[4:5], v[110:111], v[4:5], v[112:113] op_sel_hi:[0,1,0]
	v_pk_mul_f32 v[6:7], v[14:15], v[6:7]
	v_pk_fma_f32 v[8:9], v[110:111], v[8:9], v[112:113] op_sel_hi:[0,1,0]
	v_pk_fma_f32 v[2:3], v[110:111], v[2:3], v[112:113] op_sel_hi:[0,1,0]
	v_pk_fma_f32 v[6:7], v[110:111], v[6:7], v[112:113] op_sel_hi:[0,1,0]
	v_bfe_u32 v10, v9, 16, 1
	v_bfe_u32 v11, v8, 16, 1
	v_bfe_u32 v12, v5, 16, 1
	v_bfe_u32 v13, v4, 16, 1
	v_add3_u32 v4, v4, v13, s53
	v_add3_u32 v5, v5, v12, s53
	v_add3_u32 v8, v8, v11, s53
	v_add3_u32 v9, v9, v10, s53
	v_bfe_u32 v10, v2, 16, 1
	v_bfe_u32 v11, v3, 16, 1
	v_bfe_u32 v12, v6, 16, 1
	v_bfe_u32 v13, v7, 16, 1
	v_add3_u32 v7, v7, v13, s53
	v_add3_u32 v6, v6, v12, s53
	v_add3_u32 v3, v3, v11, s53
	v_add3_u32 v2, v2, v10, s53
	v_lshrrev_b32_e32 v2, 16, v2
	v_lshrrev_b32_e32 v3, 16, v3
	v_lshrrev_b32_e32 v6, 16, v6
	v_lshrrev_b32_e32 v7, 16, v7
	v_and_or_b32 v93, v9, s77, v7
	v_and_or_b32 v92, v8, s77, v6
	v_and_or_b32 v91, v5, s77, v3
	v_and_or_b32 v90, v4, s77, v2
	ds_read_b128 v[2:5], v137
	ds_read_u16 v94, v247 offset:6864
	ds_read_u16 v98, v248
	ds_read_b128 v[6:9], v138
	ds_read_u16 v95, v248 offset:528
	ds_read_u16 v99, v248 offset:1056
	ds_read_b128 v[10:13], v139
	ds_read_u16 v100, v248 offset:1584
	ds_read_u16 v101, v248 offset:2112
	ds_read_b128 v[14:17], v140
	ds_read_u16 v102, v248 offset:2640
	ds_read_u16 v103, v248 offset:3168
	s_waitcnt lgkmcnt(0)
	v_lshlrev_b32_e32 v95, 16, v95
	v_lshlrev_b32_e32 v94, 16, v94
	v_mov_b32_e32 v96, v2
	v_mov_b32_e32 v97, v6
	v_pk_add_f32 v[94:95], v[94:95], v[96:97] neg_lo:[0,1] neg_hi:[0,1]
	v_mov_b32_e32 v6, v3
	v_pk_mul_f32 v[2:3], v[6:7], v[94:95]
	v_lshlrev_b32_e32 v7, 16, v99
	v_lshlrev_b32_e32 v6, 16, v98
	v_mov_b32_e32 v94, v4
	v_mov_b32_e32 v95, v8
	v_pk_add_f32 v[6:7], v[6:7], v[94:95] neg_lo:[0,1] neg_hi:[0,1]
	v_mov_b32_e32 v8, v5
	v_pk_mul_f32 v[4:5], v[8:9], v[6:7]
	v_lshlrev_b32_e32 v7, 16, v102
	v_lshlrev_b32_e32 v6, 16, v100
	v_mov_b32_e32 v8, v10
	v_mov_b32_e32 v9, v14
	v_pk_add_f32 v[6:7], v[6:7], v[8:9] neg_lo:[0,1] neg_hi:[0,1]
	v_mov_b32_e32 v14, v11
	v_lshlrev_b32_e32 v9, 16, v103
	v_lshlrev_b32_e32 v8, 16, v101
	v_mov_b32_e32 v10, v12
	v_mov_b32_e32 v11, v16
	v_pk_add_f32 v[8:9], v[8:9], v[10:11] neg_lo:[0,1] neg_hi:[0,1]
	v_mov_b32_e32 v16, v13
	v_pk_mul_f32 v[8:9], v[16:17], v[8:9]
	v_pk_fma_f32 v[4:5], v[110:111], v[4:5], v[112:113] op_sel_hi:[0,1,0]
	v_pk_mul_f32 v[6:7], v[14:15], v[6:7]
	v_pk_fma_f32 v[8:9], v[110:111], v[8:9], v[112:113] op_sel_hi:[0,1,0]
	v_pk_fma_f32 v[2:3], v[110:111], v[2:3], v[112:113] op_sel_hi:[0,1,0]
	v_pk_fma_f32 v[6:7], v[110:111], v[6:7], v[112:113] op_sel_hi:[0,1,0]
	v_bfe_u32 v10, v9, 16, 1
	v_bfe_u32 v11, v8, 16, 1
	v_bfe_u32 v12, v5, 16, 1
	v_bfe_u32 v13, v4, 16, 1
	v_add3_u32 v4, v4, v13, s53
	v_add3_u32 v5, v5, v12, s53
	v_add3_u32 v8, v8, v11, s53
	v_add3_u32 v9, v9, v10, s53
	v_bfe_u32 v10, v2, 16, 1
	v_bfe_u32 v11, v3, 16, 1
	v_bfe_u32 v12, v6, 16, 1
	v_bfe_u32 v13, v7, 16, 1
	v_add3_u32 v7, v7, v13, s53
	v_add3_u32 v6, v6, v12, s53
	v_add3_u32 v3, v3, v11, s53
	v_add3_u32 v2, v2, v10, s53
	v_lshrrev_b32_e32 v2, 16, v2
	v_lshrrev_b32_e32 v3, 16, v3
	v_lshrrev_b32_e32 v6, 16, v6
	v_lshrrev_b32_e32 v7, 16, v7
	v_and_or_b32 v97, v9, s77, v7
	v_and_or_b32 v96, v8, s77, v6
	v_and_or_b32 v95, v5, s77, v3
	v_and_or_b32 v94, v4, s77, v2
	ds_read_b128 v[2:5], v141
	ds_read_u16 v98, v248 offset:7920
	ds_read_u16 v102, v248 offset:8448
	ds_read_b128 v[6:9], v142
	ds_read_u16 v99, v248 offset:8976
	ds_read_u16 v103, v248 offset:9504
	ds_read_b128 v[10:13], v143
	ds_read_u16 v104, v248 offset:10032
	ds_read_u16 v105, v248 offset:10560
	ds_read_b128 v[14:17], v144
	ds_read_u16 v106, v248 offset:11088
	ds_read_u16 v107, v248 offset:11616
	s_waitcnt lgkmcnt(0)
	v_lshlrev_b32_e32 v99, 16, v99
	v_lshlrev_b32_e32 v98, 16, v98
	v_mov_b32_e32 v100, v2
	v_mov_b32_e32 v101, v6
	v_pk_add_f32 v[98:99], v[98:99], v[100:101] neg_lo:[0,1] neg_hi:[0,1]
	v_mov_b32_e32 v6, v3
	v_pk_mul_f32 v[2:3], v[6:7], v[98:99]
	v_lshlrev_b32_e32 v7, 16, v103
	v_lshlrev_b32_e32 v6, 16, v102
	v_mov_b32_e32 v98, v4
	v_mov_b32_e32 v99, v8
	v_pk_add_f32 v[6:7], v[6:7], v[98:99] neg_lo:[0,1] neg_hi:[0,1]
	v_mov_b32_e32 v8, v5
	v_pk_mul_f32 v[4:5], v[8:9], v[6:7]
	v_lshlrev_b32_e32 v7, 16, v106
	v_lshlrev_b32_e32 v6, 16, v104
	v_mov_b32_e32 v8, v10
	v_mov_b32_e32 v9, v14
	v_pk_add_f32 v[6:7], v[6:7], v[8:9] neg_lo:[0,1] neg_hi:[0,1]
	v_mov_b32_e32 v14, v11
	v_lshlrev_b32_e32 v9, 16, v107
	v_lshlrev_b32_e32 v8, 16, v105
	v_mov_b32_e32 v10, v12
	v_mov_b32_e32 v11, v16
	v_pk_add_f32 v[8:9], v[8:9], v[10:11] neg_lo:[0,1] neg_hi:[0,1]
	v_mov_b32_e32 v16, v13
	v_pk_mul_f32 v[8:9], v[16:17], v[8:9]
	v_pk_fma_f32 v[4:5], v[110:111], v[4:5], v[112:113] op_sel_hi:[0,1,0]
	v_pk_mul_f32 v[6:7], v[14:15], v[6:7]
	v_pk_fma_f32 v[8:9], v[110:111], v[8:9], v[112:113] op_sel_hi:[0,1,0]
	v_pk_fma_f32 v[2:3], v[110:111], v[2:3], v[112:113] op_sel_hi:[0,1,0]
	v_pk_fma_f32 v[6:7], v[110:111], v[6:7], v[112:113] op_sel_hi:[0,1,0]
	v_bfe_u32 v10, v9, 16, 1
	v_bfe_u32 v11, v8, 16, 1
	v_bfe_u32 v12, v5, 16, 1
	v_bfe_u32 v13, v4, 16, 1
	v_add3_u32 v4, v4, v13, s53
	v_add3_u32 v5, v5, v12, s53
	v_add3_u32 v8, v8, v11, s53
	v_add3_u32 v9, v9, v10, s53
	v_bfe_u32 v10, v2, 16, 1
	v_bfe_u32 v11, v3, 16, 1
	v_bfe_u32 v12, v6, 16, 1
	v_bfe_u32 v13, v7, 16, 1
	v_add3_u32 v7, v7, v13, s53
	v_add3_u32 v6, v6, v12, s53
	v_add3_u32 v3, v3, v11, s53
	v_add3_u32 v2, v2, v10, s53
	v_lshrrev_b32_e32 v2, 16, v2
	v_lshrrev_b32_e32 v3, 16, v3
	v_lshrrev_b32_e32 v6, 16, v6
	v_lshrrev_b32_e32 v7, 16, v7
	v_and_or_b32 v101, v9, s77, v7
	v_and_or_b32 v100, v8, s77, v6
	v_and_or_b32 v99, v5, s77, v3
	v_and_or_b32 v98, v4, s77, v2
	ds_read_b128 v[2:5], v145
	ds_read_u16 v102, v248 offset:16368
	ds_read_u16 v106, v248 offset:16896
	ds_read_b128 v[6:9], v146
	ds_read_u16 v103, v248 offset:17424
	ds_read_u16 v107, v248 offset:17952
	ds_read_b128 v[10:13], v147
	ds_read_u16 v108, v248 offset:18480
	ds_read_u16 v109, v248 offset:19008
	ds_read_b128 v[14:17], v148
	ds_read_u16 v111, v248 offset:19536
	ds_read_u16 v113, v248 offset:20064
	s_waitcnt lgkmcnt(0)
	v_lshlrev_b32_e32 v103, 16, v103
	v_lshlrev_b32_e32 v102, 16, v102
	v_mov_b32_e32 v104, v2
	v_mov_b32_e32 v105, v6
	v_pk_add_f32 v[102:103], v[102:103], v[104:105] neg_lo:[0,1] neg_hi:[0,1]
	v_mov_b32_e32 v6, v3
	v_pk_mul_f32 v[2:3], v[6:7], v[102:103]
	v_lshlrev_b32_e32 v7, 16, v107
	v_lshlrev_b32_e32 v6, 16, v106
	v_mov_b32_e32 v102, v4
	v_mov_b32_e32 v103, v8
	v_pk_add_f32 v[6:7], v[6:7], v[102:103] neg_lo:[0,1] neg_hi:[0,1]
	v_mov_b32_e32 v8, v5
	v_pk_mul_f32 v[4:5], v[8:9], v[6:7]
	v_lshlrev_b32_e32 v7, 16, v111
	v_lshlrev_b32_e32 v6, 16, v108
	v_mov_b32_e32 v8, v10
	v_mov_b32_e32 v9, v14
	v_pk_add_f32 v[6:7], v[6:7], v[8:9] neg_lo:[0,1] neg_hi:[0,1]
	v_mov_b32_e32 v14, v11
	v_lshlrev_b32_e32 v9, 16, v113
	v_lshlrev_b32_e32 v8, 16, v109
	v_mov_b32_e32 v10, v12
	v_mov_b32_e32 v11, v16
	v_pk_add_f32 v[8:9], v[8:9], v[10:11] neg_lo:[0,1] neg_hi:[0,1]
	v_mov_b32_e32 v16, v13
	v_pk_mul_f32 v[8:9], v[16:17], v[8:9]
	v_pk_fma_f32 v[4:5], v[110:111], v[4:5], v[112:113] op_sel_hi:[0,1,0]
	v_pk_mul_f32 v[6:7], v[14:15], v[6:7]
	v_pk_fma_f32 v[8:9], v[110:111], v[8:9], v[112:113] op_sel_hi:[0,1,0]
	v_pk_fma_f32 v[2:3], v[110:111], v[2:3], v[112:113] op_sel_hi:[0,1,0]
	v_pk_fma_f32 v[6:7], v[110:111], v[6:7], v[112:113] op_sel_hi:[0,1,0]
	v_bfe_u32 v10, v9, 16, 1
	v_bfe_u32 v11, v8, 16, 1
	v_bfe_u32 v12, v5, 16, 1
	v_bfe_u32 v13, v4, 16, 1
	v_add3_u32 v4, v4, v13, s53
	v_add3_u32 v5, v5, v12, s53
	v_add3_u32 v8, v8, v11, s53
	v_add3_u32 v9, v9, v10, s53
	v_bfe_u32 v10, v2, 16, 1
	v_bfe_u32 v11, v3, 16, 1
	v_bfe_u32 v12, v6, 16, 1
	v_bfe_u32 v13, v7, 16, 1
	v_add3_u32 v7, v7, v13, s53
	v_add3_u32 v6, v6, v12, s53
	v_add3_u32 v3, v3, v11, s53
	v_add3_u32 v2, v2, v10, s53
	v_lshrrev_b32_e32 v2, 16, v2
	v_lshrrev_b32_e32 v3, 16, v3
	v_lshrrev_b32_e32 v6, 16, v6
	v_lshrrev_b32_e32 v7, 16, v7
	v_and_or_b32 v105, v9, s77, v7
	v_and_or_b32 v104, v8, s77, v6
	v_and_or_b32 v103, v5, s77, v3
	v_and_or_b32 v102, v4, s77, v2
	ds_read_b128 v[2:5], v149
	ds_read_u16 v106, v248 offset:24816
	ds_read_u16 v111, v248 offset:25344
	ds_read_b128 v[6:9], v150
	ds_read_u16 v107, v248 offset:25872
	ds_read_u16 v113, v248 offset:26400
	ds_read_b128 v[10:13], v151
	ds_read_u16 v114, v248 offset:26928
	ds_read_u16 v115, v248 offset:27456
	ds_read_b128 v[14:17], v152
	ds_read_u16 v116, v248 offset:27984
	ds_read_u16 v117, v248 offset:28512
	s_waitcnt lgkmcnt(0)
	v_lshlrev_b32_e32 v107, 16, v107
	v_lshlrev_b32_e32 v106, 16, v106
	v_mov_b32_e32 v108, v2
	v_mov_b32_e32 v109, v6
	v_pk_add_f32 v[106:107], v[106:107], v[108:109] neg_lo:[0,1] neg_hi:[0,1]
	v_mov_b32_e32 v6, v3
	v_pk_mul_f32 v[2:3], v[6:7], v[106:107]
	v_lshlrev_b32_e32 v7, 16, v113
	v_lshlrev_b32_e32 v6, 16, v111
	v_mov_b32_e32 v106, v4
	v_mov_b32_e32 v107, v8
	v_pk_add_f32 v[6:7], v[6:7], v[106:107] neg_lo:[0,1] neg_hi:[0,1]
	v_mov_b32_e32 v8, v5
	v_pk_mul_f32 v[4:5], v[8:9], v[6:7]
	v_lshlrev_b32_e32 v7, 16, v116
	v_lshlrev_b32_e32 v6, 16, v114
	v_mov_b32_e32 v8, v10
	v_mov_b32_e32 v9, v14
	v_pk_add_f32 v[6:7], v[6:7], v[8:9] neg_lo:[0,1] neg_hi:[0,1]
	v_mov_b32_e32 v14, v11
	v_lshlrev_b32_e32 v9, 16, v117
	v_lshlrev_b32_e32 v8, 16, v115
	v_mov_b32_e32 v10, v12
	v_mov_b32_e32 v11, v16
	v_pk_add_f32 v[8:9], v[8:9], v[10:11] neg_lo:[0,1] neg_hi:[0,1]
	v_mov_b32_e32 v16, v13
	v_pk_mul_f32 v[8:9], v[16:17], v[8:9]
	v_pk_fma_f32 v[4:5], v[110:111], v[4:5], v[112:113] op_sel_hi:[0,1,0]
	v_pk_mul_f32 v[6:7], v[14:15], v[6:7]
	v_pk_fma_f32 v[8:9], v[110:111], v[8:9], v[112:113] op_sel_hi:[0,1,0]
	v_pk_fma_f32 v[2:3], v[110:111], v[2:3], v[112:113] op_sel_hi:[0,1,0]
	v_pk_fma_f32 v[6:7], v[110:111], v[6:7], v[112:113] op_sel_hi:[0,1,0]
	v_bfe_u32 v10, v9, 16, 1
	v_bfe_u32 v11, v8, 16, 1
	v_bfe_u32 v12, v5, 16, 1
	v_bfe_u32 v13, v4, 16, 1
	v_add3_u32 v4, v4, v13, s53
	v_add3_u32 v5, v5, v12, s53
	v_add3_u32 v8, v8, v11, s53
	v_add3_u32 v9, v9, v10, s53
	v_bfe_u32 v10, v2, 16, 1
	v_bfe_u32 v11, v3, 16, 1
	v_bfe_u32 v12, v6, 16, 1
	v_bfe_u32 v13, v7, 16, 1
	v_add3_u32 v7, v7, v13, s53
	v_add3_u32 v6, v6, v12, s53
	v_add3_u32 v3, v3, v11, s53
	v_add3_u32 v2, v2, v10, s53
	v_lshrrev_b32_e32 v2, 16, v2
	v_lshrrev_b32_e32 v3, 16, v3
	v_lshrrev_b32_e32 v6, 16, v6
	v_lshrrev_b32_e32 v7, 16, v7
	v_and_or_b32 v109, v9, s77, v7
	v_and_or_b32 v108, v8, s77, v6
	v_and_or_b32 v107, v5, s77, v3
	v_and_or_b32 v106, v4, s77, v2
	ds_read_b128 v[6:9], v153
	ds_read_u16 v114, v248 offset:33264
	ds_read_u16 v116, v248 offset:33792
	ds_read_b128 v[10:13], v154
	ds_read_u16 v115, v248 offset:34320
	ds_read_u16 v117, v248 offset:34848
	ds_read_b128 v[2:5], v155
	ds_read_u16 v113, v248 offset:35376
	ds_read_u16 v111, v248 offset:35904
	ds_read_b128 v[14:17], v156
	ds_read_u16 v235, v248 offset:36432
	s_waitcnt lgkmcnt(0)
	v_lshlrev_b32_e32 v115, 16, v115
	v_lshlrev_b32_e32 v114, 16, v114
	v_mov_b32_e32 v206, v6
	v_mov_b32_e32 v207, v10
	v_pk_add_f32 v[114:115], v[114:115], v[206:207] neg_lo:[0,1] neg_hi:[0,1]
	v_lshlrev_b32_e32 v117, 16, v117
	v_lshlrev_b32_e32 v116, 16, v116
	v_mov_b32_e32 v206, v8
	v_mov_b32_e32 v207, v12
	v_pk_add_f32 v[116:117], v[116:117], v[206:207] neg_lo:[0,1] neg_hi:[0,1]
	ds_read_u16 v206, v248 offset:36960
	v_mov_b32_e32 v10, v7
	v_mov_b32_e32 v12, v9
	v_pk_mul_f32 v[6:7], v[10:11], v[114:115]
	v_pk_mul_f32 v[8:9], v[12:13], v[116:117]
	v_lshlrev_b32_e32 v11, 16, v235
	v_lshlrev_b32_e32 v10, 16, v113
	v_mov_b32_e32 v12, v2
	v_mov_b32_e32 v13, v14
	v_pk_add_f32 v[10:11], v[10:11], v[12:13] neg_lo:[0,1] neg_hi:[0,1]
	v_mov_b32_e32 v14, v3
	v_pk_mul_f32 v[2:3], v[14:15], v[10:11]
	s_waitcnt lgkmcnt(0)
	v_lshlrev_b32_e32 v11, 16, v206
	v_lshlrev_b32_e32 v10, 16, v111
	v_mov_b32_e32 v12, v4
	v_mov_b32_e32 v13, v16
	v_pk_fma_f32 v[8:9], v[110:111], v[8:9], v[112:113] op_sel_hi:[0,1,0]
	v_pk_add_f32 v[10:11], v[10:11], v[12:13] neg_lo:[0,1] neg_hi:[0,1]
	v_mov_b32_e32 v16, v5
	v_pk_mul_f32 v[4:5], v[16:17], v[10:11]
	v_bfe_u32 v12, v9, 16, 1
	v_bfe_u32 v13, v8, 16, 1
	s_barrier
	s_waitcnt vmcnt(9)
	v_pk_fma_f32 v[6:7], v[110:111], v[6:7], v[112:113] op_sel_hi:[0,1,0]
	v_pk_fma_f32 v[2:3], v[110:111], v[2:3], v[112:113] op_sel_hi:[0,1,0]
	v_pk_fma_f32 v[4:5], v[110:111], v[4:5], v[112:113] op_sel_hi:[0,1,0]
	v_add3_u32 v110, v8, v13, s53
	v_add3_u32 v111, v9, v12, s53
	ds_read_b128 v[12:15], v249
	v_bfe_u32 v10, v5, 16, 1
	v_bfe_u32 v11, v4, 16, 1
	v_add3_u32 v4, v4, v11, s53
	v_add3_u32 v5, v5, v10, s53
	v_bfe_u32 v9, v7, 16, 1
	v_bfe_u32 v10, v2, 16, 1
	v_bfe_u32 v11, v3, 16, 1
	v_add3_u32 v3, v3, v11, s53
	v_add3_u32 v2, v2, v10, s53
	v_add3_u32 v206, v7, v9, s53
	v_bfe_u32 v8, v6, 16, 1
	v_lshrrev_b32_e32 v2, 16, v2
	v_lshrrev_b32_e32 v3, 16, v3
	ds_read_b128 v[114:117], v249 offset:32
	v_lshrrev_b32_e32 v206, 16, v206
	v_add3_u32 v207, v6, v8, s53
	v_and_or_b32 v113, v5, s77, v3
	v_and_or_b32 v112, v4, s77, v2
	v_and_or_b32 v111, v111, s77, v206
	ds_read_b32 v206, v157
	s_waitcnt lgkmcnt(0)
	v_mfma_f32_32x32x16_bf16 v[2:17], v[12:15], v[82:85], 0
	v_lshrrev_b32_e32 v207, 16, v207
	v_and_or_b32 v110, v110, s77, v207
	s_lshl_b32 s0, s20, 12
	s_sub_i32 s0, s17, s0
	s_ashr_i32 s1, s0, 31
	v_mfma_f32_32x32x16_bf16 v[2:17], v[114:117], v[86:89], v[2:17]
	ds_read_b128 v[114:117], v249 offset:64
	s_waitcnt lgkmcnt(0)
	v_mfma_f32_32x32x16_bf16 v[2:17], v[114:117], v[90:93], v[2:17]
	ds_read_b128 v[114:117], v249 offset:96
	s_waitcnt lgkmcnt(0)
	v_mfma_f32_32x32x16_bf16 v[2:17], v[114:117], v[94:97], v[2:17]
	ds_read_b128 v[114:117], v249 offset:128
	s_waitcnt lgkmcnt(0)
	v_mfma_f32_32x32x16_bf16 v[2:17], v[114:117], v[98:101], v[2:17]
	ds_read_b128 v[114:117], v249 offset:160
	s_waitcnt lgkmcnt(0)
	v_mfma_f32_32x32x16_bf16 v[2:17], v[114:117], v[102:105], v[2:17]
	ds_read_b128 v[114:117], v249 offset:192
	s_waitcnt lgkmcnt(0)
	v_mfma_f32_32x32x16_bf16 v[2:17], v[114:117], v[106:109], v[2:17]
	ds_read_b128 v[114:117], v249 offset:224
	s_waitcnt lgkmcnt(0)
	v_mfma_f32_32x32x16_bf16 v[2:17], v[114:117], v[110:113], v[2:17]
	s_nop 11
	v_add_f32_e32 v2, v2, v206
	ds_write_b32 v250, v2
	ds_read_b32 v2, v158
	s_waitcnt lgkmcnt(0)
	v_add_f32_e32 v2, v3, v2
	ds_write_b32 v204, v2
	ds_read_b32 v2, v159
	s_waitcnt lgkmcnt(0)
	v_add_f32_e32 v2, v4, v2
	ds_write_b32 v204, v2 offset:144
	ds_read_b32 v2, v160
	s_waitcnt lgkmcnt(0)
	v_add_f32_e32 v2, v5, v2
	ds_write_b32 v204, v2 offset:288
	ds_read_b32 v2, v161
	s_waitcnt lgkmcnt(0)
	v_add_f32_e32 v2, v6, v2
	ds_write_b32 v204, v2 offset:1008
	ds_read_b32 v2, v162
	s_waitcnt lgkmcnt(0)
	v_add_f32_e32 v2, v7, v2
	ds_write_b32 v204, v2 offset:1152
	ds_read_b32 v2, v163
	s_waitcnt lgkmcnt(0)
	v_add_f32_e32 v2, v8, v2
	ds_write_b32 v204, v2 offset:1296
	ds_read_b32 v2, v164
	s_waitcnt lgkmcnt(0)
	v_add_f32_e32 v2, v9, v2
	ds_write_b32 v204, v2 offset:1440
	ds_read_b32 v2, v165
	s_waitcnt lgkmcnt(0)
	v_add_f32_e32 v2, v10, v2
	ds_write_b32 v204, v2 offset:2160
	ds_read_b32 v2, v166
	s_waitcnt lgkmcnt(0)
	v_add_f32_e32 v2, v11, v2
	ds_write_b32 v204, v2 offset:2304
	ds_read_b32 v2, v167
	s_waitcnt lgkmcnt(0)
	v_add_f32_e32 v2, v12, v2
	ds_write_b32 v204, v2 offset:2448
	ds_read_b32 v2, v168
	s_waitcnt lgkmcnt(0)
	v_add_f32_e32 v2, v13, v2
	ds_write_b32 v204, v2 offset:2592
	ds_read_b32 v2, v169
	s_waitcnt lgkmcnt(0)
	v_add_f32_e32 v2, v14, v2
	ds_write_b32 v204, v2 offset:3312
	ds_read_b32 v2, v170
	s_waitcnt lgkmcnt(0)
	v_add_f32_e32 v2, v15, v2
	ds_write_b32 v204, v2 offset:3456
	ds_read_b32 v2, v171
	s_waitcnt lgkmcnt(0)
	v_add_f32_e32 v2, v16, v2
	ds_write_b32 v204, v2 offset:3600
	ds_read_b32 v2, v172
	s_waitcnt lgkmcnt(0)
	v_add_f32_e32 v2, v17, v2
	ds_write_b32 v204, v2 offset:3744
	ds_read_b128 v[2:5], v249 offset:8704
	ds_read_b128 v[114:117], v249 offset:8736
	s_waitcnt lgkmcnt(0)
	v_mfma_f32_32x32x16_bf16 v[2:17], v[2:5], v[82:85], 0
	v_mfma_f32_32x32x16_bf16 v[2:17], v[114:117], v[86:89], v[2:17]
	ds_read_b128 v[114:117], v249 offset:8768
	s_waitcnt lgkmcnt(0)
	v_mfma_f32_32x32x16_bf16 v[2:17], v[114:117], v[90:93], v[2:17]
	ds_read_b128 v[114:117], v249 offset:8800
	s_waitcnt lgkmcnt(0)
	v_mfma_f32_32x32x16_bf16 v[2:17], v[114:117], v[94:97], v[2:17]
	ds_read_b128 v[114:117], v249 offset:8832
	s_waitcnt lgkmcnt(0)
	v_mfma_f32_32x32x16_bf16 v[2:17], v[114:117], v[98:101], v[2:17]
	ds_read_b128 v[114:117], v249 offset:8864
	s_waitcnt lgkmcnt(0)
	v_mfma_f32_32x32x16_bf16 v[2:17], v[114:117], v[102:105], v[2:17]
	ds_read_b128 v[114:117], v249 offset:8896
	s_waitcnt lgkmcnt(0)
	v_mfma_f32_32x32x16_bf16 v[2:17], v[114:117], v[106:109], v[2:17]
	ds_read_b128 v[114:117], v249 offset:8928
	ds_read_b32 v206, v173
	s_waitcnt lgkmcnt(0)
	v_mfma_f32_32x32x16_bf16 v[2:17], v[114:117], v[110:113], v[2:17]
	s_nop 11
	v_add_f32_e32 v2, v2, v206
	ds_write_b32 v204, v2 offset:4464
	ds_read_b32 v2, v174
	s_waitcnt lgkmcnt(0)
	v_add_f32_e32 v2, v3, v2
	ds_write_b32 v204, v2 offset:4608
	ds_read_b32 v2, v175
	s_waitcnt lgkmcnt(0)
	v_add_f32_e32 v2, v4, v2
	ds_write_b32 v204, v2 offset:4752
	ds_read_b32 v2, v176
	s_waitcnt lgkmcnt(0)
	v_add_f32_e32 v2, v5, v2
	ds_write_b32 v204, v2 offset:4896
	ds_read_b32 v2, v177
	s_waitcnt lgkmcnt(0)
	v_add_f32_e32 v2, v6, v2
	ds_write_b32 v204, v2 offset:5616
	ds_read_b32 v2, v178
	s_waitcnt lgkmcnt(0)
	v_add_f32_e32 v2, v7, v2
	ds_write_b32 v204, v2 offset:5760
	ds_read_b32 v2, v179
	s_waitcnt lgkmcnt(0)
	v_add_f32_e32 v2, v8, v2
	ds_write_b32 v204, v2 offset:5904
	ds_read_b32 v2, v180
	s_waitcnt lgkmcnt(0)
	v_add_f32_e32 v2, v9, v2
	ds_write_b32 v204, v2 offset:6048
	ds_read_b32 v2, v181
	s_waitcnt lgkmcnt(0)
	v_add_f32_e32 v2, v10, v2
	ds_write_b32 v204, v2 offset:6768
	ds_read_b32 v2, v182
	v_lshlrev_b32_e32 v10, 16, v78
	s_waitcnt lgkmcnt(0)
	v_add_f32_e32 v2, v11, v2
	ds_write_b32 v204, v2 offset:6912
	ds_read_b32 v2, v183
	v_lshlrev_b32_e32 v11, 16, v79
	s_waitcnt lgkmcnt(0)
	v_add_f32_e32 v2, v12, v2
	ds_write_b32 v204, v2 offset:7056
	ds_read_b32 v2, v184
	s_waitcnt lgkmcnt(0)
	v_add_f32_e32 v2, v13, v2
	ds_write_b32 v204, v2 offset:7200
	ds_read_b32 v2, v185
	s_waitcnt lgkmcnt(0)
	v_add_f32_e32 v2, v14, v2
	ds_write_b32 v204, v2 offset:7920
	ds_read_b32 v3, v186
	v_lshl_or_b32 v2, s20, 7, v128
	s_waitcnt lgkmcnt(0)
	v_add_f32_e32 v3, v15, v3
	ds_write_b32 v204, v3 offset:8064
	ds_read_b32 v4, v187
	v_ashrrev_i32_e32 v3, 31, v2
	v_lshlrev_b64 v[2:3], 13, v[2:3]
	v_lshl_add_u64 v[2:3], s[78:79], 0, v[2:3]
	v_lshl_add_u64 v[2:3], s[0:1], 1, v[2:3]
	s_waitcnt lgkmcnt(0)
	v_add_f32_e32 v4, v16, v4
	ds_write_b32 v204, v4 offset:8208
	ds_read_b32 v4, v188
	v_lshl_add_u64 v[6:7], s[4:5], 1, v[2:3]
	v_lshl_add_u64 v[114:115], v[6:7], 0, v[202:203]
	s_mov_b32 s0, 0x60000
	s_waitcnt lgkmcnt(0)
	v_add_f32_e32 v2, v17, v4
	ds_write_b32 v204, v2 offset:8352
	s_waitcnt lgkmcnt(0)
	ds_read_b128 v[2:5], v205
	ds_read_b128 v[6:9], v205 offset:16
	s_waitcnt lgkmcnt(0)
	v_mov_b32_e32 v12, v2
	v_mov_b32_e32 v13, v4
	v_pk_mul_f32 v[10:11], v[12:13], v[10:11]
	v_and_b32_e32 v13, 0xffff0000, v79
	v_and_b32_e32 v12, 0xffff0000, v78
	v_mov_b32_e32 v4, v3
	v_pk_mul_f32 v[2:3], v[4:5], v[12:13]
	v_lshlrev_b32_e32 v5, 16, v81
	v_lshlrev_b32_e32 v4, 16, v80
	v_mov_b32_e32 v12, v6
	v_mov_b32_e32 v13, v8
	v_pk_mul_f32 v[4:5], v[12:13], v[4:5]
	v_and_b32_e32 v13, 0xffff0000, v81
	v_and_b32_e32 v12, 0xffff0000, v80
	v_mov_b32_e32 v8, v7
	v_pk_mul_f32 v[6:7], v[8:9], v[12:13]
	v_bfe_u32 v12, v3, 16, 1
	v_bfe_u32 v8, v7, 16, 1
	v_bfe_u32 v9, v6, 16, 1
	v_bfe_u32 v13, v2, 16, 1
	v_add3_u32 v2, v2, v13, s53
	v_add3_u32 v3, v3, v12, s53
	v_add3_u32 v6, v6, v9, s53
	v_add3_u32 v7, v7, v8, s53
	v_bfe_u32 v8, v10, 16, 1
	v_bfe_u32 v9, v11, 16, 1
	v_bfe_u32 v12, v4, 16, 1
	v_bfe_u32 v13, v5, 16, 1
	v_add3_u32 v5, v5, v13, s53
	v_add3_u32 v4, v4, v12, s53
	v_add3_u32 v9, v11, v9, s53
	v_add3_u32 v8, v10, v8, s53
	v_lshrrev_b32_e32 v8, 16, v8
	v_lshrrev_b32_e32 v9, 16, v9
	v_lshrrev_b32_e32 v4, 16, v4
	v_lshrrev_b32_e32 v5, 16, v5
	v_and_or_b32 v5, v7, s77, v5
	v_and_or_b32 v4, v6, s77, v4
	v_and_or_b32 v3, v3, s77, v9
	v_and_or_b32 v2, v2, s77, v8
	ds_read_b128 v[6:9], v205 offset:2304
	global_store_dwordx4 v[114:115], v[2:5], off
	ds_read_b128 v[2:5], v205 offset:2320
	v_lshlrev_b32_e32 v11, 16, v75
	v_lshlrev_b32_e32 v10, 16, v74
	s_waitcnt lgkmcnt(0)
	v_mov_b32_e32 v12, v6
	v_mov_b32_e32 v13, v8
	v_pk_mul_f32 v[10:11], v[12:13], v[10:11]
	v_and_b32_e32 v13, 0xffff0000, v75
	v_and_b32_e32 v12, 0xffff0000, v74
	v_mov_b32_e32 v8, v7
	v_pk_mul_f32 v[6:7], v[8:9], v[12:13]
	v_lshlrev_b32_e32 v9, 16, v77
	v_lshlrev_b32_e32 v8, 16, v76
	v_mov_b32_e32 v12, v2
	v_mov_b32_e32 v13, v4
	v_pk_mul_f32 v[8:9], v[12:13], v[8:9]
	v_and_b32_e32 v13, 0xffff0000, v77
	v_and_b32_e32 v12, 0xffff0000, v76
	v_mov_b32_e32 v4, v3
	v_pk_mul_f32 v[2:3], v[4:5], v[12:13]
	v_bfe_u32 v12, v7, 16, 1
	v_bfe_u32 v4, v3, 16, 1
	v_bfe_u32 v5, v2, 16, 1
	v_bfe_u32 v13, v6, 16, 1
	v_add3_u32 v6, v6, v13, s53
	v_add3_u32 v7, v7, v12, s53
	v_add3_u32 v2, v2, v5, s53
	v_add3_u32 v3, v3, v4, s53
	v_bfe_u32 v4, v10, 16, 1
	v_bfe_u32 v5, v11, 16, 1
	v_bfe_u32 v12, v8, 16, 1
	v_bfe_u32 v13, v9, 16, 1
	v_add3_u32 v9, v9, v13, s53
	v_add3_u32 v8, v8, v12, s53
	v_add3_u32 v5, v11, v5, s53
	v_add3_u32 v4, v10, v4, s53
	v_lshrrev_b32_e32 v10, 16, v4
	v_lshrrev_b32_e32 v11, 16, v5
	v_lshrrev_b32_e32 v4, 16, v8
	v_lshrrev_b32_e32 v5, 16, v9
	v_and_or_b32 v5, v3, s77, v5
	v_and_or_b32 v4, v2, s77, v4
	v_and_or_b32 v3, v7, s77, v11
	v_and_or_b32 v2, v6, s77, v10
	v_add_co_u32_e32 v10, vcc, s57, v114
	ds_read_b128 v[6:9], v205 offset:4608
	s_nop 0
	v_addc_co_u32_e32 v11, vcc, 0, v115, vcc
	global_store_dwordx4 v[10:11], v[2:5], off
	ds_read_b128 v[2:5], v205 offset:4624
	v_lshlrev_b32_e32 v11, 16, v71
	v_lshlrev_b32_e32 v10, 16, v70
	s_waitcnt lgkmcnt(0)
	v_mov_b32_e32 v12, v6
	v_mov_b32_e32 v13, v8
	v_pk_mul_f32 v[10:11], v[12:13], v[10:11]
	v_and_b32_e32 v13, 0xffff0000, v71
	v_and_b32_e32 v12, 0xffff0000, v70
	v_mov_b32_e32 v8, v7
	v_pk_mul_f32 v[6:7], v[8:9], v[12:13]
	v_lshlrev_b32_e32 v9, 16, v73
	v_lshlrev_b32_e32 v8, 16, v72
	v_mov_b32_e32 v12, v2
	v_mov_b32_e32 v13, v4
	v_pk_mul_f32 v[8:9], v[12:13], v[8:9]
	v_and_b32_e32 v13, 0xffff0000, v73
	v_and_b32_e32 v12, 0xffff0000, v72
	v_mov_b32_e32 v4, v3
	v_pk_mul_f32 v[2:3], v[4:5], v[12:13]
	v_bfe_u32 v12, v7, 16, 1
	v_bfe_u32 v4, v3, 16, 1
	v_bfe_u32 v5, v2, 16, 1
	v_bfe_u32 v13, v6, 16, 1
	v_add3_u32 v6, v6, v13, s53
	v_add3_u32 v7, v7, v12, s53
	v_add3_u32 v2, v2, v5, s53
	v_add3_u32 v3, v3, v4, s53
	v_bfe_u32 v4, v10, 16, 1
	v_bfe_u32 v5, v11, 16, 1
	v_bfe_u32 v12, v8, 16, 1
	v_bfe_u32 v13, v9, 16, 1
	v_add3_u32 v9, v9, v13, s53
	v_add3_u32 v8, v8, v12, s53
	v_add3_u32 v5, v11, v5, s53
	v_add3_u32 v4, v10, v4, s53
	v_lshrrev_b32_e32 v10, 16, v4
	v_lshrrev_b32_e32 v11, 16, v5
	v_lshrrev_b32_e32 v4, 16, v8
	v_lshrrev_b32_e32 v5, 16, v9
	v_and_or_b32 v5, v3, s77, v5
	v_and_or_b32 v4, v2, s77, v4
	v_and_or_b32 v3, v7, s77, v11
	v_and_or_b32 v2, v6, s77, v10
	v_add_co_u32_e32 v10, vcc, s88, v114
	ds_read_b128 v[6:9], v205 offset:6912
	s_nop 0
	v_addc_co_u32_e32 v11, vcc, 0, v115, vcc
	global_store_dwordx4 v[10:11], v[2:5], off
	ds_read_b128 v[2:5], v205 offset:6928
	v_lshlrev_b32_e32 v11, 16, v67
	v_lshlrev_b32_e32 v10, 16, v66
	s_waitcnt lgkmcnt(0)
	v_mov_b32_e32 v12, v6
	v_mov_b32_e32 v13, v8
	v_pk_mul_f32 v[10:11], v[12:13], v[10:11]
	v_and_b32_e32 v13, 0xffff0000, v67
	v_and_b32_e32 v12, 0xffff0000, v66
	v_mov_b32_e32 v8, v7
	v_pk_mul_f32 v[6:7], v[8:9], v[12:13]
	v_lshlrev_b32_e32 v9, 16, v69
	v_lshlrev_b32_e32 v8, 16, v68
	v_mov_b32_e32 v12, v2
	v_mov_b32_e32 v13, v4
	v_pk_mul_f32 v[8:9], v[12:13], v[8:9]
	v_and_b32_e32 v13, 0xffff0000, v69
	v_and_b32_e32 v12, 0xffff0000, v68
	v_mov_b32_e32 v4, v3
	v_pk_mul_f32 v[2:3], v[4:5], v[12:13]
	v_bfe_u32 v12, v7, 16, 1
	v_bfe_u32 v4, v3, 16, 1
	v_bfe_u32 v5, v2, 16, 1
	v_bfe_u32 v13, v6, 16, 1
	v_add3_u32 v7, v7, v12, s53
	v_add3_u32 v3, v3, v4, s53
	v_bfe_u32 v4, v10, 16, 1
	v_bfe_u32 v12, v8, 16, 1
	v_add3_u32 v6, v6, v13, s53
	v_add3_u32 v2, v2, v5, s53
	v_bfe_u32 v5, v11, 16, 1
	v_bfe_u32 v13, v9, 16, 1
	v_add3_u32 v8, v8, v12, s53
	v_add3_u32 v4, v10, v4, s53
	v_add3_u32 v9, v9, v13, s53
	v_add3_u32 v5, v11, v5, s53
	v_lshrrev_b32_e32 v10, 16, v4
	v_lshrrev_b32_e32 v4, 16, v8
	v_lshrrev_b32_e32 v11, 16, v5
	v_lshrrev_b32_e32 v5, 16, v9
	v_and_or_b32 v4, v2, s77, v4
	v_and_or_b32 v2, v6, s77, v10
	v_add_co_u32_e32 v6, vcc, s0, v114
	v_and_or_b32 v5, v3, s77, v5
	v_and_or_b32 v3, v7, s77, v11
	v_addc_co_u32_e32 v7, vcc, 0, v115, vcc
	global_store_dwordx4 v[6:7], v[2:5], off
	s_waitcnt lgkmcnt(0)
	ds_read_b128 v[2:5], v249 offset:17408
	ds_read_b128 v[66:69], v249 offset:17440
	s_waitcnt lgkmcnt(0)
	v_mfma_f32_32x32x16_bf16 v[2:17], v[2:5], v[82:85], 0
	s_mov_b32 s0, 0x80000
	v_mfma_f32_32x32x16_bf16 v[2:17], v[66:69], v[86:89], v[2:17]
	ds_read_b128 v[66:69], v249 offset:17472
	s_waitcnt lgkmcnt(0)
	v_mfma_f32_32x32x16_bf16 v[2:17], v[66:69], v[90:93], v[2:17]
	ds_read_b128 v[66:69], v249 offset:17504
	s_waitcnt lgkmcnt(0)
	v_mfma_f32_32x32x16_bf16 v[2:17], v[66:69], v[94:97], v[2:17]
	ds_read_b128 v[66:69], v249 offset:17536
	s_waitcnt lgkmcnt(0)
	v_mfma_f32_32x32x16_bf16 v[2:17], v[66:69], v[98:101], v[2:17]
	ds_read_b128 v[66:69], v249 offset:17568
	s_waitcnt lgkmcnt(0)
	v_mfma_f32_32x32x16_bf16 v[2:17], v[66:69], v[102:105], v[2:17]
	ds_read_b128 v[66:69], v249 offset:17600
	s_waitcnt lgkmcnt(0)
	v_mfma_f32_32x32x16_bf16 v[2:17], v[66:69], v[106:109], v[2:17]
	ds_read_b128 v[66:69], v249 offset:17632
	ds_read_b32 v70, v189
	s_waitcnt lgkmcnt(0)
	v_mfma_f32_32x32x16_bf16 v[2:17], v[66:69], v[110:113], v[2:17]
	s_nop 11
	v_add_f32_e32 v2, v2, v70
	ds_write_b32 v250, v2
	ds_read_b32 v2, v190
	s_waitcnt lgkmcnt(0)
	v_add_f32_e32 v2, v3, v2
	ds_write_b32 v204, v2
	ds_read_b32 v2, v191
	s_waitcnt lgkmcnt(0)
	v_add_f32_e32 v2, v4, v2
	ds_write_b32 v204, v2 offset:144
	ds_read_b32 v2, v192
	s_waitcnt lgkmcnt(0)
	v_add_f32_e32 v2, v5, v2
	ds_write_b32 v204, v2 offset:288
	ds_read_b32 v2, v193
	s_waitcnt lgkmcnt(0)
	v_add_f32_e32 v2, v6, v2
	ds_write_b32 v204, v2 offset:1008
	ds_read_b32 v2, v194
	s_waitcnt lgkmcnt(0)
	v_add_f32_e32 v2, v7, v2
	ds_write_b32 v204, v2 offset:1152
	ds_read_b32 v2, v195
	s_waitcnt lgkmcnt(0)
	v_add_f32_e32 v2, v8, v2
	ds_write_b32 v204, v2 offset:1296
	ds_read_b32 v2, v196
	s_waitcnt lgkmcnt(0)
	v_add_f32_e32 v2, v9, v2
	ds_write_b32 v204, v2 offset:1440
	ds_read_b32 v2, v197
	s_waitcnt lgkmcnt(0)
	v_add_f32_e32 v2, v10, v2
	ds_write_b32 v204, v2 offset:2160
	ds_read_b32 v2, v198
	s_waitcnt lgkmcnt(0)
	v_add_f32_e32 v2, v11, v2
	ds_write_b32 v204, v2 offset:2304
	ds_read_b32 v2, v199
	s_waitcnt lgkmcnt(0)
	v_add_f32_e32 v2, v12, v2
	ds_write_b32 v204, v2 offset:2448
	ds_read_b32 v2, v200
	s_waitcnt lgkmcnt(0)
	v_add_f32_e32 v2, v13, v2
	ds_write_b32 v204, v2 offset:2592
	ds_read_b32 v2, v201
	s_waitcnt lgkmcnt(0)
	v_add_f32_e32 v2, v14, v2
	ds_write_b32 v204, v2 offset:3312
	ds_read_b32 v2, v208
	s_waitcnt lgkmcnt(0)
	v_add_f32_e32 v2, v15, v2
	ds_write_b32 v204, v2 offset:3456
	ds_read_b32 v2, v209
	s_waitcnt lgkmcnt(0)
	v_add_f32_e32 v2, v16, v2
	ds_write_b32 v204, v2 offset:3600
	ds_read_b32 v2, v210
	s_waitcnt lgkmcnt(0)
	v_add_f32_e32 v2, v17, v2
	ds_write_b32 v204, v2 offset:3744
	ds_read_b128 v[2:5], v249 offset:26112
	ds_read_b128 v[66:69], v249 offset:26144
	s_waitcnt lgkmcnt(0)
	v_mfma_f32_32x32x16_bf16 v[2:17], v[2:5], v[82:85], 0
	v_mfma_f32_32x32x16_bf16 v[2:17], v[66:69], v[86:89], v[2:17]
	ds_read_b128 v[66:69], v249 offset:26176
	s_waitcnt lgkmcnt(0)
	v_mfma_f32_32x32x16_bf16 v[2:17], v[66:69], v[90:93], v[2:17]
	ds_read_b128 v[66:69], v249 offset:26208
	s_waitcnt lgkmcnt(0)
	v_mfma_f32_32x32x16_bf16 v[2:17], v[66:69], v[94:97], v[2:17]
	ds_read_b128 v[66:69], v249 offset:26240
	s_waitcnt lgkmcnt(0)
	v_mfma_f32_32x32x16_bf16 v[2:17], v[66:69], v[98:101], v[2:17]
	ds_read_b128 v[66:69], v249 offset:26272
	s_waitcnt lgkmcnt(0)
	v_mfma_f32_32x32x16_bf16 v[2:17], v[66:69], v[102:105], v[2:17]
	ds_read_b128 v[66:69], v249 offset:26304
	s_waitcnt lgkmcnt(0)
	v_mfma_f32_32x32x16_bf16 v[2:17], v[66:69], v[106:109], v[2:17]
	ds_read_b128 v[66:69], v249 offset:26336
	ds_read_b32 v70, v211
	s_waitcnt lgkmcnt(0)
	v_mfma_f32_32x32x16_bf16 v[2:17], v[66:69], v[110:113], v[2:17]
	s_nop 11
	v_add_f32_e32 v2, v2, v70
	ds_write_b32 v204, v2 offset:4464
	ds_read_b32 v2, v212
	s_waitcnt lgkmcnt(0)
	v_add_f32_e32 v2, v3, v2
	ds_write_b32 v204, v2 offset:4608
	ds_read_b32 v2, v213
	s_waitcnt lgkmcnt(0)
	v_add_f32_e32 v2, v4, v2
	ds_write_b32 v204, v2 offset:4752
	ds_read_b32 v2, v214
	s_waitcnt lgkmcnt(0)
	v_add_f32_e32 v2, v5, v2
	ds_write_b32 v204, v2 offset:4896
	ds_read_b32 v2, v215
	s_waitcnt lgkmcnt(0)
	v_add_f32_e32 v2, v6, v2
	ds_write_b32 v204, v2 offset:5616
	ds_read_b32 v2, v216
	s_waitcnt lgkmcnt(0)
	v_add_f32_e32 v2, v7, v2
	ds_write_b32 v204, v2 offset:5760
	ds_read_b32 v2, v217
	s_waitcnt lgkmcnt(0)
	v_add_f32_e32 v2, v8, v2
	ds_write_b32 v204, v2 offset:5904
	ds_read_b32 v2, v218
	s_waitcnt lgkmcnt(0)
	v_add_f32_e32 v2, v9, v2
	ds_write_b32 v204, v2 offset:6048
	ds_read_b32 v2, v219
	s_waitcnt lgkmcnt(0)
	v_add_f32_e32 v2, v10, v2
	ds_write_b32 v204, v2 offset:6768
	ds_read_b32 v2, v220
	v_lshlrev_b32_e32 v10, 16, v62
	s_waitcnt lgkmcnt(0)
	v_add_f32_e32 v2, v11, v2
	ds_write_b32 v204, v2 offset:6912
	ds_read_b32 v2, v221
	v_lshlrev_b32_e32 v11, 16, v63
	s_waitcnt lgkmcnt(0)
	v_add_f32_e32 v2, v12, v2
	ds_write_b32 v204, v2 offset:7056
	ds_read_b32 v2, v222
	s_waitcnt lgkmcnt(0)
	v_add_f32_e32 v2, v13, v2
	ds_write_b32 v204, v2 offset:7200
	ds_read_b32 v2, v223
	s_waitcnt lgkmcnt(0)
	v_add_f32_e32 v2, v14, v2
	ds_write_b32 v204, v2 offset:7920
	ds_read_b32 v2, v224
	s_waitcnt lgkmcnt(0)
	v_add_f32_e32 v2, v15, v2
	ds_write_b32 v204, v2 offset:8064
	ds_read_b32 v2, v225
	s_waitcnt lgkmcnt(0)
	v_add_f32_e32 v2, v16, v2
	ds_write_b32 v204, v2 offset:8208
	ds_read_b32 v2, v226
	s_waitcnt lgkmcnt(0)
	v_add_f32_e32 v2, v17, v2
	ds_write_b32 v204, v2 offset:8352
	s_waitcnt lgkmcnt(0)
	ds_read_b128 v[2:5], v205
	ds_read_b128 v[6:9], v205 offset:16
	s_waitcnt lgkmcnt(0)
	v_mov_b32_e32 v12, v2
	v_mov_b32_e32 v13, v4
	v_pk_mul_f32 v[10:11], v[12:13], v[10:11]
	v_and_b32_e32 v13, 0xffff0000, v63
	v_and_b32_e32 v12, 0xffff0000, v62
	v_mov_b32_e32 v4, v3
	v_pk_mul_f32 v[2:3], v[4:5], v[12:13]
	v_lshlrev_b32_e32 v5, 16, v65
	v_lshlrev_b32_e32 v4, 16, v64
	v_mov_b32_e32 v12, v6
	v_mov_b32_e32 v13, v8
	v_pk_mul_f32 v[4:5], v[12:13], v[4:5]
	v_and_b32_e32 v13, 0xffff0000, v65
	v_and_b32_e32 v12, 0xffff0000, v64
	v_mov_b32_e32 v8, v7
	v_pk_mul_f32 v[6:7], v[8:9], v[12:13]
	v_bfe_u32 v12, v3, 16, 1
	v_bfe_u32 v8, v7, 16, 1
	v_bfe_u32 v9, v6, 16, 1
	v_bfe_u32 v13, v2, 16, 1
	v_add3_u32 v2, v2, v13, s53
	v_add3_u32 v3, v3, v12, s53
	v_add3_u32 v6, v6, v9, s53
	v_add3_u32 v7, v7, v8, s53
	v_bfe_u32 v8, v10, 16, 1
	v_bfe_u32 v9, v11, 16, 1
	v_bfe_u32 v12, v4, 16, 1
	v_bfe_u32 v13, v5, 16, 1
	v_add3_u32 v5, v5, v13, s53
	v_add3_u32 v4, v4, v12, s53
	v_add3_u32 v9, v11, v9, s53
	v_add3_u32 v8, v10, v8, s53
	v_lshrrev_b32_e32 v8, 16, v8
	v_lshrrev_b32_e32 v9, 16, v9
	v_lshrrev_b32_e32 v4, 16, v4
	v_lshrrev_b32_e32 v5, 16, v5
	v_and_or_b32 v5, v7, s77, v5
	v_and_or_b32 v4, v6, s77, v4
	v_and_or_b32 v3, v3, s77, v9
	v_and_or_b32 v2, v2, s77, v8
	v_add_co_u32_e32 v10, vcc, s0, v114
	ds_read_b128 v[6:9], v205 offset:2304
	s_nop 0
	v_addc_co_u32_e32 v11, vcc, 0, v115, vcc
	global_store_dwordx4 v[10:11], v[2:5], off
	ds_read_b128 v[2:5], v205 offset:2320
	v_lshlrev_b32_e32 v11, 16, v59
	v_lshlrev_b32_e32 v10, 16, v58
	s_waitcnt lgkmcnt(0)
	v_mov_b32_e32 v12, v6
	v_mov_b32_e32 v13, v8
	v_pk_mul_f32 v[10:11], v[12:13], v[10:11]
	v_and_b32_e32 v13, 0xffff0000, v59
	v_and_b32_e32 v12, 0xffff0000, v58
	v_mov_b32_e32 v8, v7
	v_pk_mul_f32 v[6:7], v[8:9], v[12:13]
	v_lshlrev_b32_e32 v9, 16, v61
	v_lshlrev_b32_e32 v8, 16, v60
	v_mov_b32_e32 v12, v2
	v_mov_b32_e32 v13, v4
	v_pk_mul_f32 v[8:9], v[12:13], v[8:9]
	v_and_b32_e32 v13, 0xffff0000, v61
	v_and_b32_e32 v12, 0xffff0000, v60
	v_mov_b32_e32 v4, v3
	v_pk_mul_f32 v[2:3], v[4:5], v[12:13]
	v_bfe_u32 v12, v7, 16, 1
	v_bfe_u32 v4, v3, 16, 1
	v_bfe_u32 v5, v2, 16, 1
	v_bfe_u32 v13, v6, 16, 1
	v_add3_u32 v6, v6, v13, s53
	v_add3_u32 v7, v7, v12, s53
	v_add3_u32 v2, v2, v5, s53
	v_add3_u32 v3, v3, v4, s53
	v_bfe_u32 v4, v10, 16, 1
	v_bfe_u32 v5, v11, 16, 1
	v_bfe_u32 v12, v8, 16, 1
	v_bfe_u32 v13, v9, 16, 1
	v_add3_u32 v9, v9, v13, s53
	v_add3_u32 v8, v8, v12, s53
	v_add3_u32 v5, v11, v5, s53
	v_add3_u32 v4, v10, v4, s53
	v_lshrrev_b32_e32 v10, 16, v4
	v_lshrrev_b32_e32 v11, 16, v5
	v_lshrrev_b32_e32 v4, 16, v8
	v_lshrrev_b32_e32 v5, 16, v9
	s_mov_b32 s0, 0xa0000
	v_and_or_b32 v5, v3, s77, v5
	v_and_or_b32 v4, v2, s77, v4
	v_and_or_b32 v3, v7, s77, v11
	v_and_or_b32 v2, v6, s77, v10
	v_add_co_u32_e32 v10, vcc, s0, v114
	ds_read_b128 v[6:9], v205 offset:4608
	s_nop 0
	v_addc_co_u32_e32 v11, vcc, 0, v115, vcc
	global_store_dwordx4 v[10:11], v[2:5], off
	ds_read_b128 v[2:5], v205 offset:4624
	v_lshlrev_b32_e32 v11, 16, v55
	v_lshlrev_b32_e32 v10, 16, v54
	s_waitcnt lgkmcnt(0)
	v_mov_b32_e32 v12, v6
	v_mov_b32_e32 v13, v8
	v_pk_mul_f32 v[10:11], v[12:13], v[10:11]
	v_and_b32_e32 v13, 0xffff0000, v55
	v_and_b32_e32 v12, 0xffff0000, v54
	v_mov_b32_e32 v8, v7
	v_pk_mul_f32 v[6:7], v[8:9], v[12:13]
	v_lshlrev_b32_e32 v9, 16, v57
	v_lshlrev_b32_e32 v8, 16, v56
	v_mov_b32_e32 v12, v2
	v_mov_b32_e32 v13, v4
	v_pk_mul_f32 v[8:9], v[12:13], v[8:9]
	v_and_b32_e32 v13, 0xffff0000, v57
	v_and_b32_e32 v12, 0xffff0000, v56
	v_mov_b32_e32 v4, v3
	v_pk_mul_f32 v[2:3], v[4:5], v[12:13]
	v_bfe_u32 v12, v7, 16, 1
	v_bfe_u32 v4, v3, 16, 1
	v_bfe_u32 v5, v2, 16, 1
	v_bfe_u32 v13, v6, 16, 1
	v_add3_u32 v6, v6, v13, s53
	v_add3_u32 v7, v7, v12, s53
	v_add3_u32 v2, v2, v5, s53
	v_add3_u32 v3, v3, v4, s53
	v_bfe_u32 v4, v10, 16, 1
	v_bfe_u32 v5, v11, 16, 1
	v_bfe_u32 v12, v8, 16, 1
	v_bfe_u32 v13, v9, 16, 1
	v_add3_u32 v9, v9, v13, s53
	v_add3_u32 v8, v8, v12, s53
	v_add3_u32 v5, v11, v5, s53
	v_add3_u32 v4, v10, v4, s53
	v_lshrrev_b32_e32 v10, 16, v4
	v_lshrrev_b32_e32 v11, 16, v5
	v_lshrrev_b32_e32 v4, 16, v8
	v_lshrrev_b32_e32 v5, 16, v9
	s_mov_b32 s0, 0xc0000
	v_and_or_b32 v5, v3, s77, v5
	v_and_or_b32 v4, v2, s77, v4
	v_and_or_b32 v3, v7, s77, v11
	v_and_or_b32 v2, v6, s77, v10
	v_add_co_u32_e32 v10, vcc, s0, v114
	ds_read_b128 v[6:9], v205 offset:6912
	s_nop 0
	v_addc_co_u32_e32 v11, vcc, 0, v115, vcc
	global_store_dwordx4 v[10:11], v[2:5], off
	ds_read_b128 v[2:5], v205 offset:6928
	v_lshlrev_b32_e32 v11, 16, v51
	v_lshlrev_b32_e32 v10, 16, v50
	s_waitcnt lgkmcnt(0)
	v_mov_b32_e32 v12, v6
	v_mov_b32_e32 v13, v8
	v_pk_mul_f32 v[10:11], v[12:13], v[10:11]
	v_and_b32_e32 v13, 0xffff0000, v51
	v_and_b32_e32 v12, 0xffff0000, v50
	v_mov_b32_e32 v8, v7
	v_pk_mul_f32 v[6:7], v[8:9], v[12:13]
	v_lshlrev_b32_e32 v9, 16, v53
	v_lshlrev_b32_e32 v8, 16, v52
	v_mov_b32_e32 v12, v2
	v_mov_b32_e32 v13, v4
	v_pk_mul_f32 v[8:9], v[12:13], v[8:9]
	v_and_b32_e32 v13, 0xffff0000, v53
	v_and_b32_e32 v12, 0xffff0000, v52
	v_mov_b32_e32 v4, v3
	v_pk_mul_f32 v[2:3], v[4:5], v[12:13]
	v_bfe_u32 v12, v7, 16, 1
	v_bfe_u32 v4, v3, 16, 1
	v_bfe_u32 v5, v2, 16, 1
	v_bfe_u32 v13, v6, 16, 1
	v_add3_u32 v7, v7, v12, s53
	v_add3_u32 v3, v3, v4, s53
	v_bfe_u32 v4, v10, 16, 1
	v_bfe_u32 v12, v8, 16, 1
	v_add3_u32 v6, v6, v13, s53
	v_add3_u32 v2, v2, v5, s53
	v_bfe_u32 v5, v11, 16, 1
	v_bfe_u32 v13, v9, 16, 1
	v_add3_u32 v8, v8, v12, s53
	v_add3_u32 v4, v10, v4, s53
	v_add3_u32 v9, v9, v13, s53
	v_add3_u32 v5, v11, v5, s53
	v_lshrrev_b32_e32 v10, 16, v4
	v_lshrrev_b32_e32 v4, 16, v8
	s_mov_b32 s0, 0xe0000
	v_lshrrev_b32_e32 v11, 16, v5
	v_lshrrev_b32_e32 v5, 16, v9
	v_and_or_b32 v4, v2, s77, v4
	v_and_or_b32 v2, v6, s77, v10
	v_add_co_u32_e32 v6, vcc, s0, v114
	s_add_u32 s0, s78, s8
	v_and_or_b32 v5, v3, s77, v5
	v_and_or_b32 v3, v7, s77, v11
	v_addc_co_u32_e32 v7, vcc, 0, v115, vcc
	s_addc_u32 s1, s79, s9
	global_store_dwordx4 v[6:7], v[2:5], off
	s_add_u32 s0, s0, s10
	s_waitcnt lgkmcnt(0)
	s_addc_u32 s1, s1, s11
	s_add_u32 s8, s0, 0x20000
	s_nop 4
	global_load_dwordx4 v[78:81], v130, s[0:1]
	s_addc_u32 s9, s1, 0
	s_nop 4
	global_load_dwordx4 v[74:77], v130, s[8:9]
	s_add_u32 s8, s0, 0x40000
	s_addc_u32 s9, s1, 0
	s_nop 4
	global_load_dwordx4 v[70:73], v130, s[8:9]
	s_add_u32 s8, s0, 0x60000
	s_addc_u32 s9, s1, 0
	s_nop 4
	global_load_dwordx4 v[66:69], v130, s[8:9]
	s_add_u32 s8, s0, 0x80000
	s_addc_u32 s9, s1, 0
	s_nop 4
	global_load_dwordx4 v[62:65], v130, s[8:9]
	s_add_u32 s8, s0, 0xa0000
	s_addc_u32 s9, s1, 0
	s_nop 4
	global_load_dwordx4 v[58:61], v130, s[8:9]
	s_add_u32 s8, s0, 0xc0000
	s_addc_u32 s9, s1, 0
	s_nop 4
	global_load_dwordx4 v[54:57], v130, s[8:9]
	s_add_u32 s0, s0, 0xe0000
	s_addc_u32 s1, s1, 0
	s_nop 4
	global_load_dwordx4 v[50:53], v130, s[0:1]
	s_add_i32 s17, s17, s14
	s_add_i32 s16, s16, s15
	s_and_b64 vcc, exec, s[6:7]
	s_barrier
	s_cbranch_vccz .LBB0_634
	s_mov_b32 s10, s19
	s_branch .LBB0_625
